# K swizzle registers patched right after their definitions in the attention item prologue (tiles 0/1 written in the new layout directly): drops the per-item K tile re-staging (2 loads + vmcnt(0) + barr
# speedup vs baseline: 1.0080x; 1.0018x over previous
; __device__ __forceinline__ int tidx() { int t = threadIdx.x; asm volatile("" : "+v"(t)); return t; }
; __device__ __forceinline__ void attn_dv256_body(const bf16* __restrict__ Qb, const bf16* __restrict__ Kh, const bf16* __restrict__ Vh,
;                                                 float* __restrict__ Ob, int seq, float kmax, char* lds) {
;     ...
;   const int tid = tidx(), wid = tid >> 6, lane = tid & 63, r32 = lane & 31, hi = lane >> 5;
;   const int rg = wid & 3, kh = wid >> 2;
;   char* V_lds = lds; char* K_lds = lds + 65536; char* XCH = lds + 98304; float* LI = (float*)(lds + 131072);
;   f32x16 o[4] = {}; bf16x8 qr[8];
;   const bf16* Qw = Qb + (long)(rg * 32 + r32) * LDQ + hi * 8;
; #pragma unroll
;   for (int d0 = 0; d0 < 8; ++d0) qr[d0] = St::ld8(Qw + d0 * 16);
;   float qq = 0.f;
; #pragma unroll
;   for (int d0 = 0; d0 < 8; ++d0)
; #pragma unroll
;     for (int e = 0; e < 8; ++e) { const float v = __uint_as_float(((unsigned)(unsigned short)qr[d0][e]) << 16); qq += v * v; }
;   qq += __shfl_xor(qq, 32);
;   constexpr float C = SCALE * 1.4426950408889634f;
;   const float mC = -sqrtf(qq) * kmax * C * 1.002f;
.LBB0_909:
	s_mul_i32 s7, s84, 0x4080
	s_mul_hi_u32 s1, s84, 0x4080
	s_add_u32 s7, s78, s7
	s_addc_u32 s1, s79, s1
	s_lshl_b32 s22, s34, 7
	s_ashr_i32 s23, s22, 31
	s_lshl_b64 s[38:39], s[22:23], 1
	s_add_u32 s42, s7, s38
	s_addc_u32 s43, s1, s39
	s_lshl_b32 s0, s0, 1
	s_add_u32 s7, s78, s0
	s_addc_u32 s13, s79, 0
	s_add_u32 s0, s7, s38
	s_addc_u32 s1, s13, s39
	s_add_u32 s38, s0, 0x2800
	s_addc_u32 s39, s1, 0
	s_and_b32 s0, s22, 0xffffff00
	s_ashr_i32 s1, s0, 31
	s_lshl_b64 s[0:1], s[0:1], 1
	s_add_u32 s0, s7, s0
	s_addc_u32 s1, s13, s1
	s_add_u32 s40, s0, 0x3000
	s_addc_u32 s41, s1, 0
	s_ashr_i32 s35, s34, 31
	s_lshl_b64 s[0:1], s[34:35], 2
	s_add_u32 s0, s20, s0
	s_addc_u32 s1, s21, s1
	v_mov_b32_e32 v3, v170
	global_load_dword v6, v165, s[0:1]
	s_mov_b64 s[0:1], 0x2000
	v_ashrrev_i32_e32 v2, 6, v3
	v_lshlrev_b32_e32 v0, 5, v2
	v_and_b32_e32 v186, 31, v3
	v_and_b32_e32 v185, 0x60, v0
	v_or_b32_e32 v0, v185, v186
	v_mul_u32_u24_e32 v0, 0x2040, v0
	v_bfe_u32 v184, v3, 5, 1
	v_lshlrev_b32_e32 v164, 1, v0
	v_lshl_add_u64 v[0:1], s[42:43], 0, v[164:165]
	v_lshlrev_b32_e32 v164, 4, v184
	v_lshl_add_u64 v[0:1], v[0:1], 0, v[164:165]
	v_add_co_u32_e32 v4, vcc, s95, v0
	s_mov_b32 s22, 0xf800000
	s_nop 0
	v_addc_co_u32_e32 v5, vcc, 0, v1, vcc
	global_load_dwordx4 v[80:83], v[4:5], off
	v_lshl_add_u64 v[0:1], v[0:1], 0, s[0:1]
	global_load_dwordx4 v[84:87], v[0:1], off offset:32
	global_load_dwordx4 v[88:91], v[0:1], off offset:64
	global_load_dwordx4 v[92:95], v[0:1], off offset:96
	global_load_dwordx4 v[96:99], v[0:1], off offset:128
	global_load_dwordx4 v[100:103], v[0:1], off offset:160
	global_load_dwordx4 v[104:107], v[0:1], off offset:192
	global_load_dwordx4 v[108:111], v[0:1], off offset:224
	v_ashrrev_i32_e32 v189, 4, v3
	v_add_u32_e32 v190, 32, v189
	s_movk_i32 s13, 0x2040
	s_cmp_lg_u32 0, -1
	v_ashrrev_i32_e32 v187, 8, v3
	v_and_b32_e32 v191, 63, v3
	v_lshlrev_b32_e32 v205, 4, v191
	v_mov_b32_e32 v132, 0
	v_mov_b32_e32 v144, 0
	v_mov_b32_e32 v192, 0
	s_mov_b32 s7, 0
	v_lshlrev_b32_e32 v209, 11, v2
	v_mov_b32_e32 v2, v192
	v_mov_b32_e32 v55, v192
	v_mov_b32_e32 v56, v192
	v_mov_b32_e32 v57, v192
	v_mov_b32_e32 v58, v192
	v_mov_b32_e32 v59, v192
	v_mov_b32_e32 v60, v192
	v_mov_b32_e32 v61, v192
	v_mov_b32_e32 v62, v192
	v_mov_b32_e32 v63, v192
	v_mov_b32_e32 v145, v144
	v_mov_b32_e32 v146, v144
	v_mov_b32_e32 v147, v144
	v_mov_b32_e32 v148, v144
	v_mov_b32_e32 v149, v144
	v_mov_b32_e32 v150, v144
	v_mov_b32_e32 v151, v144
	v_mov_b32_e32 v133, v132
	v_mov_b32_e32 v134, v132
	v_mov_b32_e32 v135, v132
	v_mov_b32_e32 v128, v132
	v_mov_b32_e32 v129, v132
	v_mov_b32_e32 v130, v132
	v_mov_b32_e32 v131, v132
	s_waitcnt vmcnt(8)
	v_mul_f32_e32 v4, 0x4f800000, v6
	v_cmp_gt_f32_e32 vcc, s22, v6
	s_waitcnt vmcnt(6)
	v_lshlrev_b32_e32 v14, 16, v84
	v_cndmask_b32_e32 v4, v6, v4, vcc
	v_sqrt_f32_e32 v7, v4
	v_lshlrev_b32_e32 v8, 16, v81
	v_and_b32_e32 v9, 0xffff0000, v81
	v_lshlrev_b32_e32 v10, 16, v82
	v_add_u32_e32 v0, -1, v7
	v_fma_f32 v1, -v0, v7, v4
	v_add_u32_e32 v5, 1, v7
	v_cmp_ge_f32_e64 s[0:1], 0, v1
	v_and_b32_e32 v1, 0xffff0000, v80
	v_fma_f32 v6, -v5, v7, v4
	v_cndmask_b32_e64 v7, v7, v0, s[0:1]
	v_lshlrev_b32_e32 v0, 16, v80
	v_mul_f32_e32 v54, v1, v1
	v_fmac_f32_e32 v54, v0, v0
	v_fmac_f32_e32 v54, v8, v8
	v_fmac_f32_e32 v54, v9, v9
	v_and_b32_e32 v11, 0xffff0000, v82
	v_fmac_f32_e32 v54, v10, v10
	v_lshlrev_b32_e32 v12, 16, v83
	v_fmac_f32_e32 v54, v11, v11
	v_and_b32_e32 v13, 0xffff0000, v83
	v_fmac_f32_e32 v54, v12, v12
	v_fmac_f32_e32 v54, v13, v13
	v_and_b32_e32 v15, 0xffff0000, v84
	v_fmac_f32_e32 v54, v14, v14
	v_lshlrev_b32_e32 v16, 16, v85
	v_fmac_f32_e32 v54, v15, v15
	v_and_b32_e32 v17, 0xffff0000, v85
	v_fmac_f32_e32 v54, v16, v16
	v_lshlrev_b32_e32 v18, 16, v86
	v_fmac_f32_e32 v54, v17, v17
	v_and_b32_e32 v19, 0xffff0000, v86
	v_fmac_f32_e32 v54, v18, v18
	v_lshlrev_b32_e32 v20, 16, v87
	v_fmac_f32_e32 v54, v19, v19
	v_and_b32_e32 v21, 0xffff0000, v87
	v_fmac_f32_e32 v54, v20, v20
	s_waitcnt vmcnt(5)
	v_lshlrev_b32_e32 v22, 16, v88
	v_fmac_f32_e32 v54, v21, v21
	v_and_b32_e32 v23, 0xffff0000, v88
	v_fmac_f32_e32 v54, v22, v22
	v_lshlrev_b32_e32 v24, 16, v89
	v_fmac_f32_e32 v54, v23, v23
	v_and_b32_e32 v25, 0xffff0000, v89
	v_fmac_f32_e32 v54, v24, v24
	v_lshlrev_b32_e32 v26, 16, v90
	v_fmac_f32_e32 v54, v25, v25
	v_and_b32_e32 v27, 0xffff0000, v90
	v_fmac_f32_e32 v54, v26, v26
	v_lshlrev_b32_e32 v28, 16, v91
	v_fmac_f32_e32 v54, v27, v27
	v_and_b32_e32 v29, 0xffff0000, v91
	v_fmac_f32_e32 v54, v28, v28
	s_waitcnt vmcnt(4)
	v_lshlrev_b32_e32 v30, 16, v92
	v_fmac_f32_e32 v54, v29, v29
	v_and_b32_e32 v31, 0xffff0000, v92
	v_fmac_f32_e32 v54, v30, v30
	v_lshlrev_b32_e32 v32, 16, v93
	v_fmac_f32_e32 v54, v31, v31
	v_and_b32_e32 v33, 0xffff0000, v93
	v_fmac_f32_e32 v54, v32, v32
	v_lshlrev_b32_e32 v34, 16, v94
	v_fmac_f32_e32 v54, v33, v33
	v_and_b32_e32 v35, 0xffff0000, v94
	v_fmac_f32_e32 v54, v34, v34
	v_lshlrev_b32_e32 v36, 16, v95
	v_fmac_f32_e32 v54, v35, v35
	v_and_b32_e32 v37, 0xffff0000, v95
	v_fmac_f32_e32 v54, v36, v36
	s_waitcnt vmcnt(3)
	v_lshlrev_b32_e32 v38, 16, v96
	v_fmac_f32_e32 v54, v37, v37
	v_and_b32_e32 v39, 0xffff0000, v96
	v_fmac_f32_e32 v54, v38, v38
	v_lshlrev_b32_e32 v40, 16, v97
	v_fmac_f32_e32 v54, v39, v39
	v_and_b32_e32 v41, 0xffff0000, v97
	v_fmac_f32_e32 v54, v40, v40
	v_lshlrev_b32_e32 v42, 16, v98
	v_fmac_f32_e32 v54, v41, v41
	v_and_b32_e32 v43, 0xffff0000, v98
	v_fmac_f32_e32 v54, v42, v42
	v_lshlrev_b32_e32 v44, 16, v99
	v_fmac_f32_e32 v54, v43, v43
	v_and_b32_e32 v45, 0xffff0000, v99
	v_fmac_f32_e32 v54, v44, v44
	s_waitcnt vmcnt(2)
; __device__ __forceinline__ int v_st(int k, int c) { const int kk = (k & ~0xC) | ((k & 4) << 1) | ((k & 8) >> 1); return ((kk >> 3) * 4 + (c >> 5)) * 512 + ((kk & 7) * 32 + (c & 31)) * 2; }
; __device__ __forceinline__ int v_rd_base(int lane) { return ((lane & 3) << 3) | (((lane >> 2) & 3) << 6) | (((lane >> 4) & 1) << 5) | (((lane >> 5) & 1) << 8); }
; #define KLOAD(k0) do { kr0 = St::ld8(&Kh[(long)((k0) + sr) * LDK + sc]); kr1 = St::ld8(&Kh[(long)((k0) + 32 + sr) * LDK + sc]); } while (0)
; #define VLOAD(k0) do { vr0 = St::ld8(&Vh[(long)((k0) + sr) * LDK + sc]); vr1 = St::ld8(&Vh[(long)((k0) + 32 + sr) * LDK + sc]); \
;     vr2 = St::ld8(&Vh[(long)((k0) + sr) * LDK + 128 + sc]); vr3 = St::ld8(&Vh[(long)((k0) + 32 + sr) * LDK + 128 + sc]); } while (0)
; #define KWRITE(b) do { *(bf16x8*)(K_lds + (b) * 16384 + KSWZ(sr, sc * 2)) = kr0; *(bf16x8*)(K_lds + (b) * 16384 + KSWZ(32 + sr, sc * 2)) = kr1; } while (0)
; #define VWRITE(b) do { *(bf16x8*)(V_lds + ((b) * 2) * 16384 + vst0) = vr0; *(bf16x8*)(V_lds + ((b) * 2) * 16384 + vst1) = vr1; \
;     *(bf16x8*)(V_lds + ((b) * 2 + 1) * 16384 + vst1) = vr2; *(bf16x8*)(V_lds + ((b) * 2 + 1) * 16384 + vst0) = vr3; } while (0)
; __device__ __forceinline__ void attn_dv256_body(const bf16* __restrict__ Qb, const bf16* __restrict__ Kh, const bf16* __restrict__ Vh,
;                                                 float* __restrict__ Ob, int seq, float kmax, char* lds) {
;     ...
;   const int sr = tid >> 4, sc = (tid & 15) * 8, vst0 = v_st(sr, sc), vst1 = v_st(32 + sr, sc);
;   const int vb0 = (int)(uintptr_t)V_lds + kh * 16384 + v_rd_base(lane);
;   bf16x8 kr0, kr1, vr0, vr1, vr2, vr3;
;     ...
;   const int NT = seq / KVBLK;
;   f32x16 pc, pn; pn = f32x16{};
;   bf16x8 q0 = {}, q1 = {}, q2 = {}, q3 = {};
;   char* XC0 = XCH;
;   KLOAD(0); VLOAD(0); asm volatile("s_waitcnt vmcnt(0)" ::: "memory"); KWRITE(0); VWRITE(0);
;   KLOAD(KVBLK); VLOAD(KVBLK); asm volatile("s_waitcnt vmcnt(0)" ::: "memory"); KWRITE(1); VWRITE(1);
;   __syncthreads();
	v_lshlrev_b32_e32 v46, 16, v100
	v_fmac_f32_e32 v54, v45, v45
	v_and_b32_e32 v47, 0xffff0000, v100
	v_fmac_f32_e32 v54, v46, v46
	v_lshlrev_b32_e32 v48, 16, v101
	v_fmac_f32_e32 v54, v47, v47
	v_and_b32_e32 v49, 0xffff0000, v101
	v_fmac_f32_e32 v54, v48, v48
	v_lshlrev_b32_e32 v50, 16, v102
	v_fmac_f32_e32 v54, v49, v49
	v_lshlrev_b32_e32 v49, 3, v3
	v_and_b32_e32 v51, 0xffff0000, v102
	v_fmac_f32_e32 v54, v50, v50
	v_and_b32_e32 v32, 0x78, v49
	v_mov_b32_e32 v33, v165
	v_lshlrev_b32_e32 v52, 16, v103
	v_fmac_f32_e32 v54, v51, v51
	v_mad_i64_i32 v[8:9], s[0:1], v189, s13, v[32:33]
	v_mad_i64_i32 v[10:11], s[0:1], v190, s13, v[32:33]
	v_and_b32_e32 v53, 0xffff0000, v103
	v_fmac_f32_e32 v54, v52, v52
	v_lshlrev_b64 v[16:17], 1, v[8:9]
	v_lshlrev_b64 v[18:19], 1, v[10:11]
	v_fmac_f32_e32 v54, v53, v53
	s_waitcnt vmcnt(1)
	v_lshlrev_b32_e32 v0, 16, v104
	v_lshl_add_u64 v[8:9], s[38:39], 0, v[16:17]
	v_lshl_add_u64 v[12:13], s[38:39], 0, v[18:19]
	v_fmac_f32_e32 v54, v0, v0
	v_and_b32_e32 v0, 0xffff0000, v104
	v_mad_i64_i32 v[24:25], s[0:1], v189, s13, 0
	v_mad_i64_i32 v[26:27], s[0:1], v190, s13, 0
	global_load_dwordx4 v[8:11], v[8:9], off
	s_nop 0
	global_load_dwordx4 v[12:15], v[12:13], off
	v_add_u32_e32 v34, 64, v189
	v_add_u32_e32 v36, 0x60, v189
	v_fmac_f32_e32 v54, v0, v0
	v_lshlrev_b32_e32 v0, 1, v32
	v_lshl_add_u64 v[24:25], v[24:25], 1, s[40:41]
	v_mov_b32_e32 v1, v165
	v_lshl_add_u64 v[26:27], v[26:27], 1, s[40:41]
	v_mad_i64_i32 v[40:41], s[0:1], v34, s13, 0
	v_mad_i64_i32 v[34:35], s[0:1], v34, s13, v[32:33]
	v_mad_i64_i32 v[32:33], s[0:1], v36, s13, v[32:33]
	v_lshl_add_u64 v[16:17], s[40:41], 0, v[16:17]
	v_lshl_add_u64 v[20:21], s[40:41], 0, v[18:19]
	v_lshl_add_u64 v[24:25], v[24:25], 0, v[0:1]
	v_lshl_add_u64 v[28:29], v[26:27], 0, v[0:1]
	v_lshlrev_b64 v[42:43], 1, v[34:35]
	v_lshlrev_b64 v[46:47], 1, v[32:33]
	global_load_dwordx4 v[16:19], v[16:17], off
	s_nop 0
	global_load_dwordx4 v[20:23], v[20:21], off
	s_nop 0
	global_load_dwordx4 v[24:27], v[24:25], off offset:256
	s_nop 0
	global_load_dwordx4 v[28:31], v[28:29], off offset:256
	s_waitcnt vmcnt(0)
	v_lshl_add_u64 v[34:35], s[38:39], 0, v[42:43]
	v_mad_i64_i32 v[44:45], s[0:1], v36, s13, 0
	v_lshl_add_u64 v[36:37], s[38:39], 0, v[46:47]
	v_lshl_add_u64 v[42:43], s[40:41], 0, v[42:43]
	v_lshl_add_u64 v[40:41], v[40:41], 1, s[40:41]
	global_load_dwordx4 v[32:35], v[34:35], off
	s_nop 0
	global_load_dwordx4 v[36:39], v[36:37], off
	v_lshl_add_u64 v[46:47], s[40:41], 0, v[46:47]
	global_load_dwordx4 v[116:119], v[42:43], off
	global_load_dwordx4 v[112:115], v[46:47], off
	v_lshl_add_u64 v[40:41], v[40:41], 0, v[0:1]
	v_lshl_add_u64 v[42:43], v[44:45], 1, s[40:41]
	v_lshl_add_u64 v[42:43], v[42:43], 0, v[0:1]
	global_load_dwordx4 v[120:123], v[40:41], off offset:256
	global_load_dwordx4 v[124:127], v[42:43], off offset:256
	v_lshlrev_b32_e32 v48, 16, v105
	v_fmac_f32_e32 v54, v48, v48
	v_and_b32_e32 v40, 0xffff0000, v105
	v_fmac_f32_e32 v54, v40, v40
	v_lshlrev_b32_e32 v40, 16, v106
	v_fmac_f32_e32 v54, v40, v40
	v_and_b32_e32 v40, 0xffff0000, v106
	v_fmac_f32_e32 v54, v40, v40
	v_lshlrev_b32_e32 v40, 16, v107
	v_fmac_f32_e32 v54, v40, v40
	v_and_b32_e32 v40, 0xffff0000, v107
	v_and_b32_e32 v41, 0xfffff0, v189
	v_lshlrev_b32_e32 v42, 1, v189
	v_fmac_f32_e32 v54, v40, v40
	s_waitcnt vmcnt(12)
	v_lshlrev_b32_e32 v40, 16, v108
	v_and_or_b32 v41, v42, 8, v41
	v_fmac_f32_e32 v54, v40, v40
	v_and_b32_e32 v40, 0xffff0000, v108
	v_lshrrev_b32_e32 v42, 1, v189
	v_lshrrev_b32_e32 v41, 1, v41
	v_bfe_u32 v43, v49, 5, 2
	v_and_b32_e32 v44, 3, v189
	v_fmac_f32_e32 v54, v40, v40
	v_lshlrev_b32_e32 v40, 16, v109
	v_or_b32_e32 v41, v41, v43
	v_and_or_b32 v42, v42, 4, v44
	v_fmac_f32_e32 v54, v40, v40
	v_and_b32_e32 v40, 0xffff0000, v109
	v_lshlrev_b32_e32 v41, 9, v41
	v_lshlrev_b32_e32 v42, 6, v42
	v_and_b32_e32 v44, 48, v0
	v_fmac_f32_e32 v54, v40, v40
	v_lshlrev_b32_e32 v40, 16, v110
	v_or3_b32 v193, v41, v42, v44
	v_and_b32_e32 v41, 0xfffff0, v190
	v_lshlrev_b32_e32 v45, 1, v190
	v_fmac_f32_e32 v54, v40, v40
	v_and_b32_e32 v40, 0xffff0000, v110
	v_and_or_b32 v41, v45, 8, v41
	v_fmac_f32_e32 v54, v40, v40
	v_lshlrev_b32_e32 v40, 16, v111
	v_lshrrev_b32_e32 v41, 1, v41
	v_fmac_f32_e32 v54, v40, v40
	v_and_b32_e32 v40, 0xffff0000, v111
	v_or_b32_e32 v41, v41, v43
	v_fmac_f32_e32 v54, v40, v40
	v_xor_b32_e32 v40, 32, v171
	v_lshlrev_b32_e32 v41, 9, v41
	v_cmp_lt_i32_e64 s[0:1], v40, v172
	v_or3_b32 v194, v41, v42, v44
	v_lshlrev_b32_e32 v41, 8, v189
	v_and_b32_e32 v42, 0x70, v3
	v_cndmask_b32_e64 v40, v171, v40, s[0:1]
	s_cselect_b32 s13, 0, 0
	v_bfe_u32 v249, v170, 8, 1
	v_lshlrev_b32_e32 v249, 7, v249
	v_bfe_u32 v250, v170, 4, 1
	v_lshlrev_b32_e32 v250, 7, v250
	v_bitop3_b32 v195, v0, v41, v42 bitop3:0xde
	v_xor_b32_e32 v195, v195, v249
	s_add_i32 s0, 0, 0x10000
	v_add_u32_e32 v41, s0, v195
	s_waitcnt vmcnt(11)
	ds_write_b128 v41, v[8:11]
	v_lshlrev_b32_e32 v8, 8, v190
	v_bitop3_b32 v196, v0, v8, v42 bitop3:0xde
	v_xor_b32_e32 v196, v196, v249
	v_add_u32_e32 v8, s0, v196
	s_waitcnt vmcnt(10)
	ds_write_b128 v8, v[12:15]
	v_add_u32_e32 v8, 0, v193
	v_add_u32_e32 v9, 0, v194
	s_add_i32 s1, 0, 0x14000
	s_waitcnt vmcnt(9)
	ds_write_b128 v8, v[16:19]
	s_waitcnt vmcnt(8)
	ds_write_b128 v9, v[20:23]
	s_waitcnt vmcnt(7)
	ds_write_b128 v9, v[24:27] offset:16384
	s_waitcnt vmcnt(6)
	ds_write_b128 v8, v[28:31] offset:16384
	v_add_u32_e32 v10, s1, v195
	s_waitcnt vmcnt(0)
	v_lshlrev_b32_e32 v12, 4, v3
	v_and_b32_e32 v16, 0x70, v12
	v_bitop3_b32 v199, v164, v16, 32 bitop3:0x36
	v_xor_b32_e32 v199, v199, v250
	s_waitcnt vmcnt(5)
	ds_write_b128 v10, v[32:35]
	v_add_u32_e32 v10, s1, v196
	s_waitcnt vmcnt(4)
	ds_write_b128 v10, v[36:39]
	s_waitcnt vmcnt(3)
	ds_write_b128 v8, v[116:119] offset:32768
	s_waitcnt vmcnt(2)
	ds_write_b128 v9, v[112:115] offset:32768
	s_waitcnt vmcnt(1)
	ds_write_b128 v9, v[120:123] offset:49152
	s_waitcnt vmcnt(0)
	ds_write_b128 v8, v[124:127] offset:49152
	v_lshlrev_b32_e32 v8, 13, v187
	v_lshlrev_b32_e32 v9, 8, v186
	v_add3_u32 v197, s0, v8, v9
	s_movk_i32 s0, 0x70
	v_bitop3_b32 v198, v164, v12, s0 bitop3:0x78
	v_xor_b32_e32 v198, v198, v250
	v_add_u32_e32 v8, v197, v198
	s_waitcnt lgkmcnt(0)
	s_barrier
; __device__ __forceinline__ int v_st(int k, int c) { const int kk = (k & ~0xC) | ((k & 4) << 1) | ((k & 8) >> 1); return ((kk >> 3) * 4 + (c >> 5)) * 512 + ((kk & 7) * 32 + (c & 31)) * 2; }
; __device__ __forceinline__ int v_rd_base(int lane) { return ((lane & 3) << 3) | (((lane >> 2) & 3) << 6) | (((lane >> 4) & 1) << 5) | (((lane >> 5) & 1) << 8); }
; #define KLOAD(k0) do { kr0 = St::ld8(&Kh[(long)((k0) + sr) * LDK + sc]); kr1 = St::ld8(&Kh[(long)((k0) + 32 + sr) * LDK + sc]); } while (0)
; #define VLOAD(k0) do { vr0 = St::ld8(&Vh[(long)((k0) + sr) * LDK + sc]); vr1 = St::ld8(&Vh[(long)((k0) + 32 + sr) * LDK + sc]); \
;     vr2 = St::ld8(&Vh[(long)((k0) + sr) * LDK + 128 + sc]); vr3 = St::ld8(&Vh[(long)((k0) + 32 + sr) * LDK + 128 + sc]); } while (0)
; #define KWRITE(b) do { *(bf16x8*)(K_lds + (b) * 16384 + KSWZ(sr, sc * 2)) = kr0; *(bf16x8*)(K_lds + (b) * 16384 + KSWZ(32 + sr, sc * 2)) = kr1; } while (0)
; #define VWRITE(b) do { *(bf16x8*)(V_lds + ((b) * 2) * 16384 + vst0) = vr0; *(bf16x8*)(V_lds + ((b) * 2) * 16384 + vst1) = vr1; \
;     *(bf16x8*)(V_lds + ((b) * 2 + 1) * 16384 + vst1) = vr2; *(bf16x8*)(V_lds + ((b) * 2 + 1) * 16384 + vst0) = vr3; } while (0)
; __device__ __forceinline__ void attn_dv256_body(const bf16* __restrict__ Qb, const bf16* __restrict__ Kh, const bf16* __restrict__ Vh,
;                                                 float* __restrict__ Ob, int seq, float kmax, char* lds) {
;     ...
;   qq += __shfl_xor(qq, 32);
;   constexpr float C = SCALE * 1.4426950408889634f;
;   const float mC = -sqrtf(qq) * kmax * C * 1.002f;
;   float l_reg = 0.f;
;   const int sr = tid >> 4, sc = (tid & 15) * 8, vst0 = v_st(sr, sc), vst1 = v_st(32 + sr, sc);
;   const int vb0 = (int)(uintptr_t)V_lds + kh * 16384 + v_rd_base(lane);
;   bf16x8 kr0, kr1, vr0, vr1, vr2, vr3;
;     ...
;   const int NT = seq / KVBLK;
;   f32x16 pc, pn; pn = f32x16{};
;   bf16x8 q0 = {}, q1 = {}, q2 = {}, q3 = {};
;   char* XC0 = XCH;
;   KLOAD(0); VLOAD(0); asm volatile("s_waitcnt vmcnt(0)" ::: "memory"); KWRITE(0); VWRITE(0);
;   KLOAD(KVBLK); VLOAD(KVBLK); asm volatile("s_waitcnt vmcnt(0)" ::: "memory"); KWRITE(1); VWRITE(1);
;   __syncthreads();
;   QKH(pc, 0);
;   KLOAD((2 < NT ? 2 : NT - 1) * KVBLK);
;   __syncthreads();
	ds_read_b128 v[8:11], v8
	v_cmp_lt_f32_e64 s[0:1], 0, v6
	v_lshlrev_b32_e32 v188, 2, v40
	ds_bpermute_b32 v40, v188, v54
	v_cndmask_b32_e64 v5, v7, v5, s[0:1]
	v_add_u32_e32 v7, v197, v199
	ds_read_b128 v[12:15], v7
	s_waitcnt lgkmcnt(2)
	v_mfma_f32_32x32x16_bf16 v[64:79], v[8:11], v[80:83], 0
	v_mul_f32_e32 v6, 0x37800000, v5
	v_cndmask_b32_e32 v5, v5, v6, vcc
	s_waitcnt lgkmcnt(1)
	v_add_f32_e32 v6, v54, v40
	v_mul_f32_e32 v7, 0x4f800000, v6
	v_cmp_gt_f32_e32 vcc, s22, v6
	v_bitop3_b32 v200, v164, v16, 64 bitop3:0x36
	v_xor_b32_e32 v200, v200, v250
	v_lshlrev_b32_e32 v3, 1, v3
	v_cndmask_b32_e32 v17, v6, v7, vcc
	v_add_u32_e32 v6, v197, v200
	ds_read_b128 v[6:9], v6
	s_waitcnt lgkmcnt(1)
	v_mfma_f32_32x32x16_bf16 v[64:79], v[12:15], v[84:87], v[64:79]
	v_mov_b32_e32 v15, 0x260
	v_cmp_class_f32_e64 s[0:1], v4, v15
	v_sqrt_f32_e32 v18, v17
	v_and_b32_e32 v3, 32, v3
	v_cndmask_b32_e64 v14, v5, v4, s[0:1]
	s_movk_i32 s0, 0x60
	v_bitop3_b32 v201, v164, v16, s0 bitop3:0x36
	v_xor_b32_e32 v201, v201, v250
	v_add_u32_e32 v5, v197, v201
	ds_read_b128 v[10:13], v5
	s_waitcnt lgkmcnt(1)
	v_mfma_f32_32x32x16_bf16 v[64:79], v[6:9], v[88:91], v[64:79]
	v_add_u32_e32 v4, -1, v18
	v_fma_f32 v5, -v4, v18, v17
	v_cmp_ge_f32_e64 s[0:1], 0, v5
	v_add_u32_e32 v9, 1, v18
	v_lshl_add_u64 v[166:167], s[38:39], 0, v[0:1]
	v_cndmask_b32_e64 v8, v18, v4, s[0:1]
	s_movk_i32 s0, 0x80
	v_bitop3_b32 v202, v164, v16, s0 bitop3:0x36
	v_xor_b32_e32 v202, v202, v250
	v_add_u32_e32 v4, v197, v202
	ds_read_b128 v[4:7], v4
	s_waitcnt lgkmcnt(1)
	v_mfma_f32_32x32x16_bf16 v[64:79], v[10:13], v[92:95], v[64:79]
	v_fma_f32 v10, -v9, v18, v17
	v_cmp_lt_f32_e64 s[0:1], 0, v10
	v_lshl_add_u64 v[168:169], s[40:41], 0, v[0:1]
	v_mov_b32_e32 v18, v192
	v_cndmask_b32_e64 v12, v8, v9, s[0:1]
	s_movk_i32 s0, 0xa0
	v_bitop3_b32 v203, v164, v16, s0 bitop3:0x36
	v_xor_b32_e32 v203, v203, v250
	v_add_u32_e32 v8, v197, v203
	ds_read_b128 v[8:11], v8
	s_waitcnt lgkmcnt(1)
	v_mfma_f32_32x32x16_bf16 v[64:79], v[4:7], v[96:99], v[64:79]
	v_mul_f32_e32 v13, 0x37800000, v12
	v_cndmask_b32_e32 v4, v12, v13, vcc
	v_cmp_class_f32_e32 vcc, v17, v15
	s_movk_i32 s0, 0xc0
	v_bitop3_b32 v204, v164, v16, s0 bitop3:0x36
	v_xor_b32_e32 v204, v204, v250
	v_cndmask_b32_e32 v4, v4, v17, vcc
	v_mul_f32_e32 v12, v14, v4
	v_add_u32_e32 v4, v197, v204
	ds_read_b128 v[4:7], v4
	s_waitcnt lgkmcnt(1)
	v_mfma_f32_32x32x16_bf16 v[64:79], v[8:11], v[100:103], v[64:79]
	s_movk_i32 s0, 0xe0
	v_bitop3_b32 v206, v164, v16, s0 bitop3:0x36
	v_xor_b32_e32 v206, v206, v250
	v_add_u32_e32 v8, v197, v206
	v_lshlrev_b32_e32 v14, 3, v191
	ds_read_b128 v[8:11], v8
	v_lshlrev_b32_e32 v13, 14, v187
	v_mul_f32_e32 v12, 0x3e0293ee, v12
	s_waitcnt lgkmcnt(1)
	v_mfma_f32_32x32x16_bf16 v[64:79], v[4:7], v[104:107], v[64:79]
	v_and_b32_e32 v4, 0xc0, v205
	v_and_or_b32 v4, v14, 24, v4
	v_and_b32_e32 v5, 0x100, v14
	v_or3_b32 v3, v4, v3, v5
	v_add3_u32 v207, v13, s13, v3
	v_add_u32_e32 v3, 0x80, v189
	v_mov_b64_e32 v[4:5], s[38:39]
	v_mad_i64_i32 v[6:7], s[22:23], v3, s93, v[4:5]
	v_add_u32_e32 v3, 0xa0, v189
	v_lshl_add_u64 v[6:7], v[6:7], 0, v[0:1]
	v_mad_i64_i32 v[4:5], s[22:23], v3, s93, v[4:5]
	v_lshl_add_u64 v[4:5], v[4:5], 0, v[0:1]
	global_load_dwordx4 v[136:139], v[6:7], off
	global_load_dwordx4 v[140:143], v[4:5], off
	s_waitcnt lgkmcnt(0)
	v_mfma_f32_32x32x16_bf16 v[64:79], v[8:11], v[108:111], v[64:79]
	v_mul_f32_e32 v208, 0xbf804189, v12
	s_add_i32 s0, s6, -1
	v_mov_b32_e32 v0, 0
	v_mov_b32_e32 v1, v192
	v_mov_b32_e32 v3, v192
	v_mov_b32_e32 v4, v192
	v_mov_b32_e32 v5, v192
	v_mov_b32_e32 v6, v192
	v_mov_b32_e32 v7, v192
	v_mov_b32_e32 v8, v192
	v_mov_b32_e32 v9, v192
	v_mov_b32_e32 v10, v192
	v_mov_b32_e32 v11, v192
	v_mov_b32_e32 v12, v192
	v_mov_b32_e32 v13, v192
	v_mov_b32_e32 v14, v192
	v_mov_b32_e32 v15, v192
	v_mov_b32_e32 v16, 0
	v_mov_b32_e32 v17, v192
	v_mov_b32_e32 v19, v192
	v_mov_b32_e32 v20, v192
	v_mov_b32_e32 v21, v192
	v_mov_b32_e32 v22, v192
	v_mov_b32_e32 v23, v192
	v_mov_b32_e32 v24, v192
	v_mov_b32_e32 v25, v192
	v_mov_b32_e32 v26, v192
	v_mov_b32_e32 v27, v192
	v_mov_b32_e32 v28, v192
	v_mov_b32_e32 v29, v192
	v_mov_b32_e32 v30, v192
	v_mov_b32_e32 v31, v192
	v_mov_b32_e32 v32, 0
	v_mov_b32_e32 v33, v192
	v_mov_b32_e32 v34, v192
	v_mov_b32_e32 v35, v192
	v_mov_b32_e32 v36, v192
	v_mov_b32_e32 v37, v192
	v_mov_b32_e32 v38, v192
	v_mov_b32_e32 v39, v192
	v_mov_b32_e32 v40, v192
	v_mov_b32_e32 v41, v192
	v_mov_b32_e32 v42, v192
	v_mov_b32_e32 v43, v192
	v_mov_b32_e32 v44, v192
	v_mov_b32_e32 v45, v192
	v_mov_b32_e32 v46, v192
	v_mov_b32_e32 v47, v192
	v_mov_b32_e32 v48, 0
	v_mov_b32_e32 v49, v192
	v_mov_b32_e32 v50, v192
	v_mov_b32_e32 v51, v192
	v_mov_b32_e32 v52, v192
	v_mov_b32_e32 v53, v192
	v_mov_b32_e32 v54, v192
	s_barrier
